# combined variant + MLA unit prologue de-serialised: the first K/V/rope-K tile DMAs are issued with the Q loads, before the rope arithmetic
# baseline (speedup 1.0000x reference)
.LBB0_41:
	s_ashr_i32 s8, s46, 7
	s_ashr_i32 s9, s8, 31
	s_lshl_b32 s13, s46, 8
	s_lshl_b64 s[6:7], s[8:9], 12
	s_and_b32 s13, s13, 0xf00
	s_or_b32 s6, s6, s13
	s_bfe_u32 s36, s46, 0x30004
	s_mul_i32 s13, s7, 0xc00
	s_mul_hi_u32 s14, s6, 0xc00
	s_lshl_b32 s12, s36, 9
	s_add_i32 s14, s14, s13
	s_mul_i32 s13, s6, 0xc00
	s_add_u32 s13, s11, s13
	s_addc_u32 s14, s24, s14
	s_mul_i32 s15, s36, 0x180
	s_add_u32 s20, s13, s15
	s_addc_u32 s21, s14, 0
	s_lshl_b64 s[14:15], s[8:9], 24
	s_add_u32 s13, s25, s14
	s_addc_u32 s33, s30, s15
	s_add_u32 s44, s13, s12
	s_addc_u32 s45, s33, 0
	s_lshl_b64 s[42:43], s[8:9], 19
	s_add_u32 s40, s31, s42
	s_addc_u32 s41, s38, s43
	s_lshl_b64 s[8:9], s[6:7], 7
	s_add_u32 s48, s39, s8
	s_addc_u32 s49, s79, s9
	s_add_u32 s50, s88, s8
	v_mov_b32_e32 v62, v203
	s_addc_u32 s51, s71, s9
	v_mov_b64_e32 v[0:1], s[20:21]
	v_readfirstlane_b32 s9, v62
	s_ashr_i32 s35, s9, 6
	v_and_b32_e32 v63, 31, v62
	s_lshl_b32 s34, s35, 5
	v_or_b32_e32 v2, s34, v63
	v_lshrrev_b32_e32 v50, 1, v62
	v_mad_i64_i32 v[0:1], s[20:21], v2, s73, v[0:1]
	v_and_b32_e32 v184, 16, v50
	v_lshl_add_u64 v[26:27], v[0:1], 0, v[184:185]
	v_lshlrev_b32_e32 v0, 5, v2
	global_load_dwordx4 v[2:5], v[26:27], off offset:256
	global_load_dwordx4 v[6:9], v[26:27], off offset:320
	v_ashrrev_i32_e32 v1, 31, v0
	v_lshlrev_b64 v[10:11], 2, v[0:1]
	v_lshl_add_u64 v[12:13], s[48:49], 0, v[10:11]
	v_and_b32_e32 v0, 32, v62
	v_mov_b32_e32 v1, v185
	v_lshl_add_u64 v[10:11], s[50:51], 0, v[10:11]
	v_lshl_add_u64 v[28:29], v[10:11], 0, v[0:1]
	v_lshl_add_u64 v[30:31], v[12:13], 0, v[0:1]
	global_load_dwordx4 v[10:13], v[28:29], off
	global_load_dwordx4 v[14:17], v[30:31], off
	global_load_dwordx4 v[18:21], v[28:29], off offset:16
	global_load_dwordx4 v[22:25], v[30:31], off offset:16
	global_load_dwordx4 v[124:127], v[26:27], off
	global_load_dwordx4 v[120:123], v[26:27], off offset:32
	global_load_dwordx4 v[116:119], v[26:27], off offset:64
	global_load_dwordx4 v[112:115], v[26:27], off offset:96
	global_load_dwordx4 v[108:111], v[26:27], off offset:128
	global_load_dwordx4 v[104:107], v[26:27], off offset:160
	global_load_dwordx4 v[100:103], v[26:27], off offset:192
	global_load_dwordx4 v[96:99], v[26:27], off offset:224
	s_and_b32 s8, s9, 0x3fffffc0
	s_lshl_b32 s8, s8, 2
	s_lshl_b32 s9, s35, 12
	v_and_b32_e32 v160, 63, v62
	s_add_i32 s37, s8, 0
	s_add_i32 s8, s9, 0
	v_lshlrev_b32_e32 v64, 4, v160
	s_add_i32 s8, s8, 0x18800
	v_add_u32_e32 v164, s8, v64
	s_lshl_b32 s20, s35, 3
	s_lshl_b32 s8, s35, 2
	s_and_b32 s8, s8, 4
	s_add_i32 s37, s37, 0x18000
	v_mov_b32_e32 v59, v185
	s_cmp_lg_u32 0, -1
	s_cselect_b32 s13, 0, 0
	v_mov_b32_e32 v155, v59
	v_bfe_u32 v74, v62, 2, 3
	v_bitop3_b32 v74, s20, -13, v74 bitop3:0xc8
	v_and_b32_e32 v75, 8, v50
	v_bfe_u32 v73, v62, 4, 2
	v_or3_b32 v74, v74, v75, s8
	v_lshlrev_b32_e32 v86, 3, v62
	v_ashrrev_i32_e32 v75, 31, v74
	v_or_b32_e32 v144, s20, v73
	v_lshlrev_b64 v[146:147], 12, v[74:75]
	v_bitop3_b32 v73, s20, v62, v73 bitop3:0x36
	v_ashrrev_i32_e32 v145, 31, v144
	v_and_or_b32 v72, v86, 24, v0
	v_or_b32_e32 v150, 4, v144
	v_lshl_add_u64 v[74:75], s[44:45], 0, v[146:147]
	v_lshlrev_b64 v[148:149], 12, v[144:145]
	v_lshlrev_b32_e32 v73, 4, v73
	v_lshlrev_b32_e32 v154, 1, v72
	v_bitop3_b32 v80, v144, v62, 4 bitop3:0x36
	v_ashrrev_i32_e32 v151, 31, v150
	v_lshl_add_u64 v[76:77], s[44:45], 0, v[148:149]
	v_and_b32_e32 v78, 0xf0, v73
	v_mov_b32_e32 v79, v185
	v_lshl_add_u64 v[72:73], v[74:75], 0, v[154:155]
	s_mov_b64 s[8:9], 0x100
	v_lshlrev_b64 v[152:153], 12, v[150:151]
	v_lshlrev_b32_e32 v80, 4, v80
	v_lshl_add_u64 v[76:77], v[76:77], 0, v[78:79]
	v_lshl_add_u64 v[74:75], v[72:73], 0, s[8:9]
	v_lshl_add_u64 v[78:79], s[44:45], 0, v[152:153]
	v_and_b32_e32 v80, 0xf0, v80
	v_mov_b32_e32 v81, v185
	s_mov_b64 s[8:9], 0x180
	s_lshl_b32 s44, s35, 11
	v_lshl_add_u64 v[78:79], v[78:79], 0, v[80:81]
	v_lshl_add_u64 v[80:81], v[72:73], 0, s[8:9]
	v_bfe_u32 v82, v62, 3, 3
	s_add_i32 s8, s13, s44
	v_or_b32_e32 v82, s20, v82
	s_add_i32 s45, s8, 0xc000
	v_lshrrev_b32_e32 v145, 1, v82
	s_mov_b32 m0, s45
	s_add_i32 s77, s8, 0xc400
	v_xor_b32_e32 v84, v145, v62
	v_ashrrev_i32_e32 v83, 31, v82
	global_load_lds_dwordx4 v[76:77], off
	s_mov_b32 m0, s77
	s_lshl_b32 s9, s35, 10
	v_lshlrev_b64 v[156:157], 7, v[82:83]
	v_lshlrev_b32_e32 v84, 4, v84
	s_or_b32 s47, s44, 0x400
	global_load_lds_dwordx4 v[78:79], off
	s_mov_b32 m0, s8
	s_add_i32 s33, s13, s9
	v_lshl_add_u64 v[82:83], s[40:41], 0, v[156:157]
	v_and_b32_e32 v84, 0x70, v84
	v_mov_b32_e32 v85, v185
	global_load_lds_dwordx4 v[74:75], off
	s_add_i32 m0, s47, s13
	s_add_i32 s9, s33, 0x14000
	v_lshl_add_u64 v[82:83], v[82:83], 0, v[84:85]
	global_load_lds_dwordx4 v[80:81], off
	s_mov_b32 m0, s9
	s_mov_b64 s[20:21], 0x40000
	s_add_i32 s93, s8, 0x10000
	global_load_lds_dwordx4 v[82:83], off
	v_lshl_add_u64 v[74:75], v[76:77], 0, s[20:21]
	s_mov_b32 m0, s93
	s_add_i32 s50, s8, 0x10400
	global_load_lds_dwordx4 v[74:75], off
	v_lshl_add_u64 v[74:75], v[78:79], 0, s[20:21]
	s_mov_b32 m0, s50
	s_mov_b64 s[20:21], 0x40100
	global_load_lds_dwordx4 v[74:75], off
	v_lshl_add_u64 v[74:75], v[72:73], 0, s[20:21]
	s_add_i32 m0, s8, 0x4000
	s_mov_b64 s[20:21], 0x40180
	global_load_lds_dwordx4 v[74:75], off
	v_lshl_add_u64 v[72:73], v[72:73], 0, s[20:21]
	s_add_i32 m0, s8, 0x4400
	s_mov_b64 s[20:21], 0x2000
	s_add_i32 s51, s33, 0x16000
	global_load_lds_dwordx4 v[72:73], off
	v_lshl_add_u64 v[72:73], v[82:83], 0, s[20:21]
	s_mov_b32 m0, s51
	global_load_lds_dwordx4 v[72:73], off
	v_or_b32_e32 v68, 0x60, v184
	v_lshlrev_b32_e32 v69, 7, v63
	s_mov_b32 s52, 0
	s_mov_b32 s53, s52
	s_mov_b32 s54, s52
	s_mov_b32 s55, s52
	s_mov_b32 s56, s52
	s_mov_b32 s57, s52
	s_mov_b32 s58, s52
	s_mov_b32 s59, s52
	s_mov_b32 s60, s52
	s_mov_b32 s61, s52
	s_mov_b32 s62, s52
	s_mov_b32 s63, s52
	s_mov_b32 s64, s52
	s_mov_b32 s65, s52
	s_mov_b32 s66, s52
	s_mov_b32 s67, s52
	v_lshl_add_u32 v162, v63, 2, s37
	s_mov_b32 s49, 2
	s_mov_b32 s48, -1
	v_mov_b32_e32 v163, 0
	s_waitcnt vmcnt(0)
	v_mov_b32_e32 v42, v12
	v_lshlrev_b32_e32 v33, 16, v2
	v_and_b32_e32 v35, 0xffff0000, v2
	v_lshlrev_b32_e32 v37, 16, v3
	v_and_b32_e32 v3, 0xffff0000, v3
	v_and_b32_e32 v2, 0xffff0000, v7
	v_mov_b32_e32 v43, v16
	v_mov_b32_e32 v44, v16
	v_mov_b32_e32 v45, v12
	v_mov_b32_e32 v16, v13
	v_mov_b32_e32 v12, v17
	v_lshlrev_b32_e32 v32, 16, v6
	v_and_b32_e32 v34, 0xffff0000, v6
	v_lshlrev_b32_e32 v36, 16, v7
	v_lshlrev_b32_e32 v7, 16, v4
	v_lshlrev_b32_e32 v6, 16, v8
	v_mov_b32_e32 v46, v18
	v_mov_b32_e32 v47, v22
	v_mov_b32_e32 v48, v22
	v_mov_b32_e32 v49, v18
	v_pk_mul_f32 v[16:17], v[16:17], v[2:3]
	v_pk_mul_f32 v[2:3], v[12:13], v[2:3]
	v_pk_mul_f32 v[12:13], v[46:47], v[6:7]
	v_sub_f32_e32 v16, v17, v16
	v_add_f32_e32 v17, v2, v3
	v_pk_mul_f32 v[2:3], v[48:49], v[6:7]
	v_sub_f32_e32 v12, v13, v12
	v_add_f32_e32 v13, v2, v3
	v_and_b32_e32 v3, 0xffff0000, v4
	v_and_b32_e32 v2, 0xffff0000, v8
	v_mov_b32_e32 v22, v19
	v_mov_b32_e32 v18, v23
	v_pk_mul_f32 v[6:7], v[22:23], v[2:3]
	v_pk_mul_f32 v[2:3], v[18:19], v[2:3]
	v_sub_f32_e32 v8, v7, v6
	v_add_f32_e32 v18, v2, v3
	v_lshlrev_b32_e32 v3, 16, v5
	v_lshlrev_b32_e32 v2, 16, v9
	v_mov_b32_e32 v6, v20
	v_mov_b32_e32 v7, v24
	v_pk_mul_f32 v[6:7], v[6:7], v[2:3]
	v_mov_b32_e32 v38, v10
	v_sub_f32_e32 v19, v7, v6
	v_mov_b32_e32 v6, v24
	v_mov_b32_e32 v7, v20
	v_pk_mul_f32 v[2:3], v[6:7], v[2:3]
	v_mov_b32_e32 v39, v14
	v_mov_b32_e32 v40, v14
	v_mov_b32_e32 v41, v10
	v_mov_b32_e32 v14, v11
	v_mov_b32_e32 v10, v15
	v_add_f32_e32 v22, v2, v3
	v_and_b32_e32 v3, 0xffff0000, v5
	v_and_b32_e32 v2, 0xffff0000, v9
	v_mov_b32_e32 v24, v21
	v_mov_b32_e32 v20, v25
	v_pk_mul_f32 v[38:39], v[38:39], v[32:33]
	v_pk_mul_f32 v[32:33], v[40:41], v[32:33]
	v_pk_mul_f32 v[14:15], v[14:15], v[34:35]
	v_pk_mul_f32 v[10:11], v[10:11], v[34:35]
	v_pk_mul_f32 v[34:35], v[42:43], v[36:37]
	v_pk_mul_f32 v[36:37], v[44:45], v[36:37]
	v_pk_mul_f32 v[4:5], v[24:25], v[2:3]
	v_pk_mul_f32 v[2:3], v[20:21], v[2:3]
	v_add_f32_e32 v32, v32, v33
	v_sub_f32_e32 v14, v15, v14
	v_add_f32_e32 v10, v10, v11
	v_sub_f32_e32 v11, v35, v34
	v_add_f32_e32 v15, v36, v37
	v_sub_f32_e32 v5, v5, v4
	v_add_f32_e32 v9, v2, v3
	v_sub_f32_e32 v1, v39, v38
	v_cvt_pk_bf16_f32 v2, v1, v14
	v_cvt_pk_bf16_f32 v3, v11, v16
	v_cvt_pk_bf16_f32 v4, v12, v8
	v_cvt_pk_bf16_f32 v5, v19, v5
	v_cvt_pk_bf16_f32 v6, v32, v10
	v_cvt_pk_bf16_f32 v7, v15, v17
	v_cvt_pk_bf16_f32 v8, v13, v18
	v_cvt_pk_bf16_f32 v9, v22, v9
	global_load_dwordx4 v[10:13], v[26:27], off offset:288
	global_load_dwordx4 v[14:17], v[26:27], off offset:352
	global_load_dwordx4 v[18:21], v[28:29], off offset:64
	global_load_dwordx4 v[22:25], v[30:31], off offset:64
	s_nop 0
	global_load_dwordx4 v[26:29], v[28:29], off offset:80
	s_nop 0
	global_load_dwordx4 v[30:33], v[30:31], off offset:80
	ds_write_b128 v164, v[2:5]
	ds_write_b128 v164, v[6:9] offset:2048
	s_waitcnt vmcnt(5)
	v_lshlrev_b32_e32 v3, 16, v10
	s_waitcnt vmcnt(4)
	v_lshlrev_b32_e32 v2, 16, v14
	s_waitcnt vmcnt(3)
	v_mov_b32_e32 v4, v18
	s_waitcnt vmcnt(2)
	v_mov_b32_e32 v5, v22
	v_mov_b32_e32 v6, v22
	v_mov_b32_e32 v7, v18
	v_and_b32_e32 v9, 0xffff0000, v10
	v_lshlrev_b32_e32 v35, 16, v11
	v_mov_b32_e32 v37, v24
	v_mov_b32_e32 v38, v24
	v_and_b32_e32 v11, 0xffff0000, v11
	v_pk_mul_f32 v[4:5], v[4:5], v[2:3]
	v_pk_mul_f32 v[2:3], v[6:7], v[2:3]
	v_and_b32_e32 v10, 0xffff0000, v15
	v_mov_b32_e32 v24, v21
	v_and_b32_e32 v8, 0xffff0000, v14
	v_mov_b32_e32 v36, v20
	v_mov_b32_e32 v39, v20
	v_add_f32_e32 v14, v2, v3
	v_pk_mul_f32 v[2:3], v[24:25], v[10:11]
	v_mov_b32_e32 v20, v25
	v_lshlrev_b32_e32 v34, 16, v15
	v_sub_f32_e32 v15, v3, v2
	v_pk_mul_f32 v[2:3], v[20:21], v[10:11]
	v_sub_f32_e32 v1, v5, v4
	v_add_f32_e32 v10, v2, v3
	v_lshlrev_b32_e32 v3, 16, v12
	v_lshlrev_b32_e32 v2, 16, v16
	s_waitcnt vmcnt(1)
	v_mov_b32_e32 v4, v26
	s_waitcnt vmcnt(0)
	v_mov_b32_e32 v5, v30
	v_pk_mul_f32 v[4:5], v[4:5], v[2:3]
	v_mov_b32_e32 v22, v19
	v_mov_b32_e32 v18, v23
	v_sub_f32_e32 v11, v5, v4
	v_mov_b32_e32 v4, v30
	v_mov_b32_e32 v5, v26
	v_pk_mul_f32 v[6:7], v[22:23], v[8:9]
	v_pk_mul_f32 v[8:9], v[18:19], v[8:9]
	v_pk_mul_f32 v[18:19], v[36:37], v[34:35]
	v_pk_mul_f32 v[2:3], v[4:5], v[2:3]
	v_sub_f32_e32 v6, v7, v6
	v_add_f32_e32 v7, v8, v9
	v_sub_f32_e32 v8, v19, v18
	v_add_f32_e32 v18, v2, v3
	v_and_b32_e32 v3, 0xffff0000, v12
	v_and_b32_e32 v2, 0xffff0000, v16
	v_mov_b32_e32 v30, v27
	v_mov_b32_e32 v26, v31
	v_pk_mul_f32 v[4:5], v[30:31], v[2:3]
	v_pk_mul_f32 v[2:3], v[26:27], v[2:3]
	v_sub_f32_e32 v12, v5, v4
	v_add_f32_e32 v16, v2, v3
	v_lshlrev_b32_e32 v3, 16, v13
	v_lshlrev_b32_e32 v2, 16, v17
	v_mov_b32_e32 v4, v28
	v_mov_b32_e32 v5, v32
	v_pk_mul_f32 v[4:5], v[4:5], v[2:3]
	v_pk_mul_f32 v[22:23], v[38:39], v[34:35]
	v_sub_f32_e32 v19, v5, v4
	v_mov_b32_e32 v4, v32
	v_mov_b32_e32 v5, v28
	v_pk_mul_f32 v[2:3], v[4:5], v[2:3]
	v_mov_b32_e32 v32, v29
	v_add_f32_e32 v20, v2, v3
	v_and_b32_e32 v3, 0xffff0000, v13
	v_and_b32_e32 v2, 0xffff0000, v17
	v_pk_mul_f32 v[4:5], v[32:33], v[2:3]
	v_mov_b32_e32 v28, v33
	v_sub_f32_e32 v5, v5, v4
	v_pk_mul_f32 v[2:3], v[28:29], v[2:3]
	v_add_f32_e32 v9, v22, v23
	v_add_f32_e32 v13, v2, v3
	v_cvt_pk_bf16_f32 v2, v1, v6
	v_cvt_pk_bf16_f32 v3, v8, v15
	v_cvt_pk_bf16_f32 v4, v11, v12
	v_cvt_pk_bf16_f32 v5, v19, v5
	v_cvt_pk_bf16_f32 v6, v14, v7
	v_cvt_pk_bf16_f32 v7, v9, v10
	v_cvt_pk_bf16_f32 v8, v18, v16
	v_cvt_pk_bf16_f32 v9, v20, v13
	ds_write_b128 v164, v[2:5] offset:1024
	ds_write_b128 v164, v[6:9] offset:3072
	v_mov_b32_e32 v14, v86
	v_mov_b32_e32 v48, v144
	v_mov_b32_e32 v49, v145
	v_mov_b32_e32 v50, v146
	v_mov_b32_e32 v51, v147
	v_mov_b32_e32 v52, v148
	v_mov_b32_e32 v53, v149
	v_mov_b32_e32 v54, v150
	v_mov_b32_e32 v55, v151
	v_mov_b32_e32 v56, v152
	v_mov_b32_e32 v57, v153
	v_mov_b32_e32 v58, v154
	v_mov_b32_e32 v60, v156
	v_mov_b32_e32 v61, v157
	v_lshlrev_b32_e32 v8, 8, v63
	v_lshlrev_b32_e32 v0, 4, v62
	v_and_b32_e32 v9, 0xf0, v0
	v_bitop3_b32 v166, v184, v8, v9 bitop3:0xde
	s_waitcnt vmcnt(0) lgkmcnt(0)
	s_barrier
	v_add_u32_e32 v167, 0, v166
	ds_read_b128 v[0:3], v167 offset:49152
	ds_read_b128 v[4:7], v167 offset:57344
	s_waitcnt lgkmcnt(0)
	v_mfma_f32_32x32x16_bf16 v[32:47], v[0:3], v[124:127], 0
	v_or_b32_e32 v55, 32, v184
	v_bitop3_b32 v168, v55, v8, v9 bitop3:0xde
	v_add_u32_e32 v169, 0, v168
	v_or_b32_e32 v59, 64, v184
	v_bitop3_b32 v170, v59, v8, v9 bitop3:0xde
	v_add_u32_e32 v171, 0, v170
	v_bitop3_b32 v172, v68, v8, v9 bitop3:0xde
	v_mfma_f32_32x32x16_bf16 v[16:31], v[4:7], v[124:127], 0
	ds_read_b128 v[0:3], v169 offset:49152
	ds_read_b128 v[4:7], v169 offset:57344
	v_add_u32_e32 v173, 0, v172
	v_and_b32_e32 v70, 0x70, v14
	v_bitop3_b32 v182, v184, v69, v70 bitop3:0xde
	s_add_i32 s8, 0, 0x14000
	v_add_u32_e32 v183, s8, v182
	v_bitop3_b32 v192, v55, v69, v70 bitop3:0xde
	s_waitcnt lgkmcnt(0)
	v_mfma_f32_32x32x16_bf16 v[32:47], v[0:3], v[120:123], v[32:47]
	v_add_u32_e32 v193, s8, v192
	v_bitop3_b32 v194, v59, v69, v70 bitop3:0xde
	v_add_u32_e32 v195, s8, v194
	v_bitop3_b32 v196, v68, v69, v70 bitop3:0xde
	v_add_u32_e32 v197, s8, v196
	v_lshl_add_u64 v[136:137], s[42:43], 0, v[60:61]
	v_lshl_add_u64 v[140:141], s[14:15], 0, v[52:53]
	v_mfma_f32_32x32x16_bf16 v[16:31], v[4:7], v[120:123], v[16:31]
	ds_read_b128 v[0:3], v171 offset:49152
	ds_read_b128 v[4:7], v171 offset:57344
	v_lshl_add_u64 v[138:139], s[14:15], 0, v[50:51]
	v_lshl_add_u64 v[142:143], s[14:15], 0, v[56:57]
	v_or3_b32 v138, v138, s12, v58
	v_cmp_gt_u32_e64 s[40:41], 32, v160
	s_waitcnt lgkmcnt(0)
	v_mfma_f32_32x32x16_bf16 v[32:47], v[0:3], v[116:119], v[32:47]
	v_mfma_f32_32x32x16_bf16 v[16:31], v[4:7], v[116:119], v[16:31]
	ds_read_b128 v[0:3], v173 offset:49152
	ds_read_b128 v[4:7], v173 offset:57344
	s_waitcnt lgkmcnt(0)
	v_mfma_f32_32x32x16_bf16 v[32:47], v[0:3], v[112:115], v[32:47]
	v_or_b32_e32 v0, 0x80, v184
	v_bitop3_b32 v174, v0, v8, v9 bitop3:0xde
	v_add_u32_e32 v175, 0, v174
	v_mfma_f32_32x32x16_bf16 v[16:31], v[4:7], v[112:115], v[16:31]
	ds_read_b128 v[0:3], v175 offset:49152
	ds_read_b128 v[4:7], v175 offset:57344
	s_waitcnt lgkmcnt(0)
	v_mfma_f32_32x32x16_bf16 v[32:47], v[0:3], v[108:111], v[32:47]
	v_or_b32_e32 v0, 0xa0, v184
	v_bitop3_b32 v176, v0, v8, v9 bitop3:0xde
	v_add_u32_e32 v177, 0, v176
	v_mfma_f32_32x32x16_bf16 v[16:31], v[4:7], v[108:111], v[16:31]
	ds_read_b128 v[0:3], v177 offset:49152
	ds_read_b128 v[4:7], v177 offset:57344
	s_waitcnt lgkmcnt(0)
	v_mfma_f32_32x32x16_bf16 v[32:47], v[0:3], v[104:107], v[32:47]
	v_or_b32_e32 v0, 0xc0, v184
	v_bitop3_b32 v178, v0, v8, v9 bitop3:0xde
	v_add_u32_e32 v179, 0, v178
	v_mfma_f32_32x32x16_bf16 v[16:31], v[4:7], v[104:107], v[16:31]
	ds_read_b128 v[0:3], v179 offset:49152
	ds_read_b128 v[4:7], v179 offset:57344
	s_waitcnt lgkmcnt(0)
	v_mfma_f32_32x32x16_bf16 v[32:47], v[0:3], v[100:103], v[32:47]
	v_or_b32_e32 v0, 0xe0, v184
	v_bitop3_b32 v180, v0, v8, v9 bitop3:0xde
	v_add_u32_e32 v181, 0, v180
	v_mfma_f32_32x32x16_bf16 v[16:31], v[4:7], v[100:103], v[16:31]
	ds_read_b128 v[0:3], v181 offset:49152
	ds_read_b128 v[4:7], v181 offset:57344
	s_waitcnt lgkmcnt(0)
	v_mfma_f32_32x32x16_bf16 v[32:47], v[0:3], v[96:99], v[32:47]
	v_mfma_f32_32x32x16_bf16 v[16:31], v[4:7], v[96:99], v[16:31]
	ds_read_b128 v[0:3], v183
	ds_read_b128 v[4:7], v164
	ds_read_b128 v[8:11], v183 offset:4096
	ds_read_b128 v[12:15], v164 offset:1024
	s_waitcnt lgkmcnt(0)
	v_mfma_f32_32x32x16_bf16 v[32:47], v[0:3], v[4:7], v[32:47]
	ds_read_b128 v[0:3], v193
	v_mfma_f32_32x32x16_bf16 v[16:31], v[8:11], v[4:7], v[16:31]
	ds_read_b128 v[4:7], v193 offset:4096
	v_lshlrev_b32_e32 v8, 3, v160
	s_waitcnt lgkmcnt(0)
	v_mfma_f32_32x32x16_bf16 v[32:47], v[0:3], v[12:15], v[32:47]
	v_and_b32_e32 v0, 0xc0, v64
	v_and_or_b32 v9, v8, 24, v0
	v_lshlrev_b32_e32 v0, 1, v62
	v_and_b32_e32 v10, 32, v0
	ds_read_b128 v[0:3], v195
	v_mfma_f32_32x32x16_bf16 v[16:31], v[4:7], v[12:15], v[16:31]
	v_and_b32_e32 v4, 0x100, v8
	v_or3_b32 v165, v9, v10, v4
	ds_read_b128 v[4:7], v164 offset:2048
	ds_read_b128 v[8:11], v195 offset:4096
	ds_read_b128 v[64:67], v164 offset:3072
	ds_read_b128 v[68:71], v197 offset:4096
	v_add_u32_e32 v161, s13, v165
	s_waitcnt lgkmcnt(0)
	v_mfma_f32_32x32x16_bf16 v[32:47], v[0:3], v[4:7], v[32:47]
	ds_read_b128 v[0:3], v197
	s_waitcnt vmcnt(0) lgkmcnt(0)
	s_barrier
	s_waitcnt lgkmcnt(0)
	v_mfma_f32_32x32x16_bf16 v[32:47], v[0:3], v[64:67], v[32:47]
	v_mfma_f32_32x32x16_bf16 v[16:31], v[8:11], v[4:7], v[16:31]
	s_nop 10
	v_max_f32_e32 v55, v33, v33
	v_max_f32_e32 v59, v32, v32
	v_max_f32_e32 v55, v59, v55
	v_max3_f32 v55, v55, v34, v35
	v_max3_f32 v55, v55, v36, v37
	v_max3_f32 v55, v55, v38, v39
	v_max3_f32 v55, v55, v40, v41
	v_mfma_f32_32x32x16_bf16 v[16:31], v[68:71], v[64:67], v[16:31]
	v_max3_f32 v55, v55, v42, v43
	v_max3_f32 v55, v55, v44, v45
	v_max3_f32 v55, v55, v46, v47
	v_mov_b64_e32 v[0:1], s[52:53]
	v_mov_b64_e32 v[14:15], s[66:67]
	v_mov_b64_e32 v[2:3], s[54:55]
	v_mov_b64_e32 v[4:5], s[56:57]
	s_nop 4
	v_max3_f32 v55, v55, v16, v17
	v_max3_f32 v55, v55, v18, v19
	v_max3_f32 v55, v55, v20, v21
	v_max3_f32 v55, v55, v22, v23
	v_max3_f32 v55, v55, v24, v25
	v_max3_f32 v55, v55, v26, v27
	v_max3_f32 v55, v55, v28, v29
	v_max3_f32 v55, v55, v30, v31
	v_mov_b32_e32 v59, v55
	s_nop 1
	v_permlane32_swap_b32_e32 v55, v59
	v_max_f32_e32 v59, v59, v59
	v_max_f32_e32 v55, v55, v55
	v_max_f32_e32 v55, v55, v59
	v_add_f32_e32 v59, 0x7149f2ca, v55
	v_cmp_ge_f32_e32 vcc, s97, v59
	s_cmp_eq_u64 vcc, exec
	v_max_f32_e32 v55, 0xf149f2ca, v55
	s_cselect_b64 vcc, -1, 0
	v_cndmask_b32_e32 v222, v55, v207, vcc
	v_sub_f32_e32 v59, 0xf149f2ca, v55
	v_mul_f32_e32 v64, 0xbf800000, v222
	v_mul_f32_e32 v59, 0x3f800000, v59
	v_pk_fma_f32 v[158:159], v[16:17], s[80:81], v[64:65] op_sel_hi:[1,0,0]
	v_bitop3_b32 v16, v49, 7, v62 bitop3:0x48
	v_exp_f32_e32 v59, v59
	v_mov_b32_e32 v55, v64
	v_lshl_or_b32 v136, v16, 4, v136
	v_bitop3_b32 v16, v48, 15, v62 bitop3:0x48
	v_fmamk_f32 v32, v32, 0x3f800000, v64
	v_fmamk_f32 v33, v33, 0x3f800000, v64
	v_fmamk_f32 v34, v34, 0x3f800000, v64
	v_fmamk_f32 v35, v35, 0x3f800000, v64
	v_fmamk_f32 v36, v36, 0x3f800000, v64
	v_fmamk_f32 v37, v37, 0x3f800000, v64
	v_fmamk_f32 v38, v38, 0x3f800000, v64
	v_fmamk_f32 v39, v39, 0x3f800000, v64
	v_fmamk_f32 v40, v40, 0x3f800000, v64
	v_fmamk_f32 v41, v41, 0x3f800000, v64
	v_fmamk_f32 v42, v42, 0x3f800000, v64
	v_fmamk_f32 v43, v43, 0x3f800000, v64
	v_fmamk_f32 v44, v44, 0x3f800000, v64
	v_fmamk_f32 v45, v45, 0x3f800000, v64
	v_fmamk_f32 v46, v46, 0x3f800000, v64
	v_fmac_f32_e32 v55, 0x3f800000, v47
	v_lshlrev_b32_e32 v16, 4, v16
	v_exp_f32_e32 v236, v32
	v_exp_f32_e32 v238, v33
	v_exp_f32_e32 v234, v34
	v_exp_f32_e32 v237, v35
	v_exp_f32_e32 v233, v36
	v_exp_f32_e32 v235, v37
	v_exp_f32_e32 v231, v38
	v_exp_f32_e32 v232, v39
	v_exp_f32_e32 v228, v40
	v_exp_f32_e32 v230, v41
	v_exp_f32_e32 v227, v42
	v_exp_f32_e32 v229, v43
	v_exp_f32_e32 v224, v44
	v_exp_f32_e32 v226, v45
	v_exp_f32_e32 v223, v46
	v_exp_f32_e32 v225, v55
	v_or3_b32 v140, v140, s12, v16
	v_bitop3_b32 v16, v54, 15, v62 bitop3:0x48
	v_lshlrev_b32_e32 v16, 4, v16
	v_mov_b64_e32 v[6:7], s[58:59]
	v_mov_b64_e32 v[8:9], s[60:61]
	v_mov_b64_e32 v[10:11], s[62:63]
	v_mov_b64_e32 v[12:13], s[64:65]
	v_cndmask_b32_e64 v198, v59, 1.0, vcc
	v_pk_fma_f32 v[128:129], v[30:31], s[80:81], v[64:65] op_sel_hi:[1,0,0]
	v_pk_fma_f32 v[130:131], v[28:29], s[80:81], v[64:65] op_sel_hi:[1,0,0]
	v_pk_fma_f32 v[132:133], v[26:27], s[80:81], v[64:65] op_sel_hi:[1,0,0]
	v_pk_fma_f32 v[134:135], v[24:25], s[80:81], v[64:65] op_sel_hi:[1,0,0]
	v_pk_fma_f32 v[152:153], v[22:23], s[80:81], v[64:65] op_sel_hi:[1,0,0]
	v_pk_fma_f32 v[154:155], v[20:21], s[80:81], v[64:65] op_sel_hi:[1,0,0]
	v_pk_fma_f32 v[156:157], v[18:19], s[80:81], v[64:65] op_sel_hi:[1,0,0]
	v_or3_b32 v142, v142, s12, v16
	v_mov_b64_e32 v[62:63], v[14:15]
	v_mov_b64_e32 v[46:47], v[14:15]
	v_mov_b64_e32 v[30:31], v[14:15]
	s_mov_b32 s53, 0x1b400000
	v_mov_b64_e32 v[60:61], v[12:13]
	v_mov_b64_e32 v[58:59], v[10:11]
	v_mov_b64_e32 v[56:57], v[8:9]
	v_mov_b64_e32 v[54:55], v[6:7]
	v_mov_b64_e32 v[52:53], v[4:5]
	v_mov_b64_e32 v[50:51], v[2:3]
	v_mov_b64_e32 v[48:49], v[0:1]
	v_mov_b64_e32 v[44:45], v[12:13]
	v_mov_b64_e32 v[42:43], v[10:11]
	v_mov_b64_e32 v[40:41], v[8:9]
	v_mov_b64_e32 v[38:39], v[6:7]
	v_mov_b64_e32 v[36:37], v[4:5]
	v_mov_b64_e32 v[34:35], v[2:3]
	v_mov_b64_e32 v[32:33], v[0:1]
	v_mov_b64_e32 v[28:29], v[12:13]
	v_mov_b64_e32 v[26:27], v[10:11]
	v_mov_b64_e32 v[24:25], v[8:9]
	v_mov_b64_e32 v[22:23], v[6:7]
	v_mov_b64_e32 v[20:21], v[4:5]
	v_mov_b64_e32 v[18:19], v[2:3]
	v_mov_b64_e32 v[16:17], v[0:1]
